# GEMM K-loop: load segments run at s_setprio 2 (above the MFMA segments at 1) so ds_read / LDS-DMA issue is not starved
# speedup vs baseline: 1.0009x; 1.0009x over previous
; #define PG8_STAGE(bufoff, gbase, voff) do { _Pragma("unroll") for (int _i = 0; _i < 2; ++_i) \
;         __builtin_amdgcn_global_load_lds((const unsigned*)((const char*)(gbase) + (voff)[_i]), (PG8_LAS unsigned*)(lds + (bufoff) + ldsw + _i * 8192), 16, 0, 0); } while (0)
; #define PG8_LDA(dst, b, h) do { _Pragma("unroll") for (int m = 0; m < 4; ++m) _Pragma("unroll") for (int k = 0; k < 2; ++k) dst[m][k] = *(const PG8_LAS bf16x8*)(lds + PG8_SA(b, h) + aoff + m * 2048 + k * 1024); } while (0)
; #define PG8_LDB(dst, b, h) do { _Pragma("unroll") for (int n = 0; n < 2; ++n) _Pragma("unroll") for (int k = 0; k < 2; ++k) dst[n][k] = *(const PG8_LAS bf16x8*)(lds + PG8_SB(b, h) + boff + n * 2048 + k * 1024); } while (0)
; #define PG8_WAIT_V(n) asm volatile("s_waitcnt vmcnt(" #n ")" ::: "memory")
; #define PG8_WAIT_L(n) asm volatile("s_waitcnt lgkmcnt(" #n ")" ::: "memory")
; #define PG8_BAR __builtin_amdgcn_s_barrier()
; #define PG8_SCHED __builtin_amdgcn_sched_barrier(0)
; template <class Epi, class Sched, bool ALIGN_EPI = false, bool SP2 = false>
; __device__ __forceinline__ void gemm_phase(PG8_LAS unsigned char* lds, const Gemm g, const Sched& S, const Epi& E) {
;     ...
;         const char* nA = has_next ? (const char*)g.A + (size_t)nxt.pm * tstep : cA; const char* nB = has_next ? (const char*)g.Bt + (size_t)nxt.pn * tstep : cB;
;         for (int t = 0; t < nt; t += 2) {
;             const bool last = (t == nt - 2);
;             const char* a1 = cA + (size_t)(t + 1) * kstepB;
;             const char* a2 = last ? nA : cA + (size_t)(t + 2) * kstepB; const char* b2 = last ? nB : cB + (size_t)(t + 2) * kstepB;
;             const char* a3 = a2 + kstepB; const char* b3 = b2 + kstepB;
;             if (last && has_next) S.a_ready(nxt);
;             if constexpr (SP2) {
;             PG8_LDB(B0, 0, 0); PG8_LDB(B1, 0, 1); PG8_SCHED; PG8_LDA(At, 0, 0); PG8_STAGE(PG8_SA(1, 1), a1 + hstepB, voffA);
;             PG8_WAIT_V(8); PG8_WAIT_L(0); PG8_BAR; PG8_MMA(0, 0, At, B0); PG8_MMA(0, 1, At, B1); PG8_BAR; PG8_SCHED;
;             PG8_LDA(At, 0, 1); PG8_STAGE(PG8_SB(0, 0), b2, voffB); PG8_STAGE(PG8_SB(0, 1), b2 + hstepB, voffB); PG8_STAGE(PG8_SA(0, 0), a2, voffA);
;             PG8_WAIT_V(8); PG8_WAIT_L(0); PG8_BAR; PG8_MMA(1, 0, At, B0); PG8_MMA(1, 1, At, B1); PG8_BAR; PG8_SCHED;
.LBB0_193:
	s_add_i32 s84, s38, 2
	s_add_u32 s39, s36, 0x4000
	s_addc_u32 s40, s37, 0
	s_cmp_eq_u32 s31, s38
	s_cselect_b32 s42, s8, s39
	s_cselect_b32 s43, s9, s40
	s_cselect_b32 s40, s62, s78
	s_cselect_b32 s41, s63, s82
	s_add_u32 s38, s42, 0x8000
	s_addc_u32 s39, s43, 0
	s_add_i32 s90, 0, 0x10000
	s_add_i32 s64, 0, 0x14000
	v_add_u32_e32 v140, s90, v174
	v_add_u32_e32 v161, s64, v174
	ds_read_b128 v[128:131], v140
	ds_read_b128 v[132:135], v140 offset:1024
	ds_read_b128 v[136:139], v140 offset:2048
	ds_read_b128 v[140:143], v140 offset:3072
	ds_read_b128 v[144:147], v161
	ds_read_b128 v[148:151], v161 offset:1024
	ds_read_b128 v[178:181], v161 offset:2048
	ds_read_b128 v[182:185], v161 offset:3072
	v_lshl_add_u64 v[172:173], s[36:37], 0, v[168:169]
	s_add_i32 m0, s21, 0xc000
	ds_read_b128 v[186:189], v177
	ds_read_b128 v[190:193], v177 offset:1024
	ds_read_b128 v[194:197], v177 offset:2048
	ds_read_b128 v[198:201], v177 offset:3072
	ds_read_b128 v[202:205], v177 offset:4096
	ds_read_b128 v[206:209], v177 offset:5120
	ds_read_b128 v[210:213], v177 offset:6144
	ds_read_b128 v[214:217], v177 offset:7168
	global_load_lds_dwordx4 v[172:173], off
	v_lshl_add_u64 v[172:173], s[36:37], 0, v[170:171]
	s_add_i32 m0, s21, 0xe000
	s_nop 0
	global_load_lds_dwordx4 v[172:173], off
	s_waitcnt vmcnt(8)
	s_waitcnt lgkmcnt(0)
	s_barrier
	s_setprio 1
	s_waitcnt lgkmcnt(0)
	v_mfma_f32_16x16x32_bf16 v[124:127], v[128:131], v[186:189], v[124:127]
	v_mfma_f32_16x16x32_bf16 v[124:127], v[132:135], v[190:193], v[124:127]
	v_mfma_f32_16x16x32_bf16 v[120:123], v[136:139], v[186:189], v[120:123]
	v_mfma_f32_16x16x32_bf16 v[120:123], v[140:143], v[190:193], v[120:123]
	v_mfma_f32_16x16x32_bf16 v[108:111], v[128:131], v[194:197], v[108:111]
	v_mfma_f32_16x16x32_bf16 v[108:111], v[132:135], v[198:201], v[108:111]
	v_mfma_f32_16x16x32_bf16 v[104:107], v[136:139], v[194:197], v[104:107]
	v_mfma_f32_16x16x32_bf16 v[104:107], v[140:143], v[198:201], v[104:107]
	v_mfma_f32_16x16x32_bf16 v[92:95], v[128:131], v[202:205], v[92:95]
	v_mfma_f32_16x16x32_bf16 v[92:95], v[132:135], v[206:209], v[92:95]
	v_mfma_f32_16x16x32_bf16 v[88:91], v[136:139], v[202:205], v[88:91]
	v_mfma_f32_16x16x32_bf16 v[88:91], v[140:143], v[206:209], v[88:91]
	v_mfma_f32_16x16x32_bf16 v[76:79], v[128:131], v[210:213], v[76:79]
	v_mfma_f32_16x16x32_bf16 v[76:79], v[132:135], v[214:217], v[76:79]
	v_mfma_f32_16x16x32_bf16 v[72:75], v[136:139], v[210:213], v[72:75]
	v_mfma_f32_16x16x32_bf16 v[72:75], v[140:143], v[214:217], v[72:75]
	s_setprio 0
	s_setprio 1
	v_mfma_f32_16x16x32_bf16 v[116:119], v[144:147], v[186:189], v[116:119]
	v_mfma_f32_16x16x32_bf16 v[116:119], v[148:151], v[190:193], v[116:119]
	v_mfma_f32_16x16x32_bf16 v[112:115], v[178:181], v[186:189], v[112:115]
	v_mfma_f32_16x16x32_bf16 v[112:115], v[182:185], v[190:193], v[112:115]
	v_mfma_f32_16x16x32_bf16 v[100:103], v[144:147], v[194:197], v[100:103]
	v_mfma_f32_16x16x32_bf16 v[100:103], v[148:151], v[198:201], v[100:103]
	v_mfma_f32_16x16x32_bf16 v[96:99], v[178:181], v[194:197], v[96:99]
	v_mfma_f32_16x16x32_bf16 v[96:99], v[182:185], v[198:201], v[96:99]
	v_mfma_f32_16x16x32_bf16 v[84:87], v[144:147], v[202:205], v[84:87]
	v_mfma_f32_16x16x32_bf16 v[84:87], v[148:151], v[206:209], v[84:87]
	v_mfma_f32_16x16x32_bf16 v[80:83], v[178:181], v[202:205], v[80:83]
	v_mfma_f32_16x16x32_bf16 v[80:83], v[182:185], v[206:209], v[80:83]
	v_mfma_f32_16x16x32_bf16 v[68:71], v[144:147], v[210:213], v[68:71]
	v_mfma_f32_16x16x32_bf16 v[68:71], v[148:151], v[214:217], v[68:71]
	v_mfma_f32_16x16x32_bf16 v[64:67], v[178:181], v[210:213], v[64:67]
	v_mfma_f32_16x16x32_bf16 v[64:67], v[182:185], v[214:217], v[64:67]
	s_setprio 2
	s_barrier
	s_add_i32 s65, s90, s20
	v_lshl_add_u64 v[172:173], s[40:41], 0, v[156:157]
	s_mov_b32 m0, s65
	ds_read_b128 v[186:189], v177 offset:16384
	ds_read_b128 v[190:193], v177 offset:17408
	ds_read_b128 v[194:197], v177 offset:18432
	ds_read_b128 v[198:201], v177 offset:19456
	ds_read_b128 v[202:205], v177 offset:20480
	ds_read_b128 v[206:209], v177 offset:21504
	ds_read_b128 v[210:213], v177 offset:22528
	ds_read_b128 v[214:217], v177 offset:23552
	global_load_lds_dwordx4 v[172:173], off
	s_add_i32 m0, s65, 0x2000
	s_add_u32 vcc_lo, s40, 0x4000
	v_lshl_add_u64 v[172:173], s[40:41], 0, v[152:153]
	s_addc_u32 vcc_hi, s41, 0
	s_add_i32 s64, s64, s20
	global_load_lds_dwordx4 v[172:173], off
	v_lshl_add_u64 v[172:173], vcc, 0, v[156:157]
	s_mov_b32 m0, s64
	s_nop 0
	global_load_lds_dwordx4 v[172:173], off
	v_lshl_add_u64 v[172:173], vcc, 0, v[152:153]
	s_add_i32 m0, s64, 0x2000
	s_nop 0
	global_load_lds_dwordx4 v[172:173], off
	v_lshl_add_u64 v[172:173], s[42:43], 0, v[158:159]
	s_mov_b32 m0, s21
	s_nop 0
	global_load_lds_dwordx4 v[172:173], off
	v_lshl_add_u64 v[172:173], s[42:43], 0, v[154:155]
	s_mov_b32 m0, s22
	s_nop 0
	global_load_lds_dwordx4 v[172:173], off
	s_waitcnt vmcnt(8)
	s_waitcnt lgkmcnt(0)
	s_barrier
; #define PG8_STAGE(bufoff, gbase, voff) do { _Pragma("unroll") for (int _i = 0; _i < 2; ++_i) \
;         __builtin_amdgcn_global_load_lds((const unsigned*)((const char*)(gbase) + (voff)[_i]), (PG8_LAS unsigned*)(lds + (bufoff) + ldsw + _i * 8192), 16, 0, 0); } while (0)
; #define PG8_LDA(dst, b, h) do { _Pragma("unroll") for (int m = 0; m < 4; ++m) _Pragma("unroll") for (int k = 0; k < 2; ++k) dst[m][k] = *(const PG8_LAS bf16x8*)(lds + PG8_SA(b, h) + aoff + m * 2048 + k * 1024); } while (0)
; #define PG8_LDB(dst, b, h) do { _Pragma("unroll") for (int n = 0; n < 2; ++n) _Pragma("unroll") for (int k = 0; k < 2; ++k) dst[n][k] = *(const PG8_LAS bf16x8*)(lds + PG8_SB(b, h) + boff + n * 2048 + k * 1024); } while (0)
; #define PG8_MMA(ai, bj, At, Bt) do { __builtin_amdgcn_s_setprio(1); _Pragma("unroll") for (int m = 0; m < 4; ++m) _Pragma("unroll") for (int n = 0; n < 2; ++n) _Pragma("unroll") for (int k = 0; k < 2; ++k) \
;         acc[ai][bj][m][n] = __builtin_amdgcn_mfma_f32_16x16x32_bf16(Bt[n][k], At[m][k], acc[ai][bj][m][n], 0, 0, 0); __builtin_amdgcn_s_setprio(0); } while (0)
; #define PG8_WAIT_V(n) asm volatile("s_waitcnt vmcnt(" #n ")" ::: "memory")
; #define PG8_WAIT_L(n) asm volatile("s_waitcnt lgkmcnt(" #n ")" ::: "memory")
; #define PG8_BAR __builtin_amdgcn_s_barrier()
; #define PG8_SCHED __builtin_amdgcn_sched_barrier(0)
; template <class Epi, class Sched, bool ALIGN_EPI = false, bool SP2 = false>
; __device__ __forceinline__ void gemm_phase(PG8_LAS unsigned char* lds, const Gemm g, const Sched& S, const Epi& E) {
;     ...
;             PG8_WAIT_V(8); PG8_WAIT_L(0); PG8_BAR; PG8_MMA(1, 0, At, B0); PG8_MMA(1, 1, At, B1); PG8_BAR; PG8_SCHED;
;             PG8_LDB(B0, 1, 0); PG8_LDB(B1, 1, 1); PG8_SCHED; PG8_LDA(At, 1, 0); PG8_STAGE(PG8_SA(0, 1), a2 + hstepB, voffA);
;             PG8_WAIT_V(8); PG8_WAIT_L(0); PG8_BAR; PG8_MMA(0, 0, At, B0); PG8_MMA(0, 1, At, B1); PG8_BAR; PG8_SCHED;
	s_setprio 1
	s_waitcnt lgkmcnt(0)
	v_mfma_f32_16x16x32_bf16 v[60:63], v[128:131], v[186:189], v[60:63]
	v_mfma_f32_16x16x32_bf16 v[60:63], v[132:135], v[190:193], v[60:63]
	v_mfma_f32_16x16x32_bf16 v[56:59], v[136:139], v[186:189], v[56:59]
	v_mfma_f32_16x16x32_bf16 v[56:59], v[140:143], v[190:193], v[56:59]
	v_mfma_f32_16x16x32_bf16 v[44:47], v[128:131], v[194:197], v[44:47]
	v_mfma_f32_16x16x32_bf16 v[44:47], v[132:135], v[198:201], v[44:47]
	v_mfma_f32_16x16x32_bf16 v[40:43], v[136:139], v[194:197], v[40:43]
	v_mfma_f32_16x16x32_bf16 v[40:43], v[140:143], v[198:201], v[40:43]
	v_mfma_f32_16x16x32_bf16 v[28:31], v[128:131], v[202:205], v[28:31]
	v_mfma_f32_16x16x32_bf16 v[28:31], v[132:135], v[206:209], v[28:31]
	v_mfma_f32_16x16x32_bf16 v[24:27], v[136:139], v[202:205], v[24:27]
	v_mfma_f32_16x16x32_bf16 v[24:27], v[140:143], v[206:209], v[24:27]
	v_mfma_f32_16x16x32_bf16 v[12:15], v[128:131], v[210:213], v[12:15]
	v_mfma_f32_16x16x32_bf16 v[12:15], v[132:135], v[214:217], v[12:15]
	v_mfma_f32_16x16x32_bf16 v[8:11], v[136:139], v[210:213], v[8:11]
	v_mfma_f32_16x16x32_bf16 v[8:11], v[140:143], v[214:217], v[8:11]
	s_setprio 0
	s_setprio 1
	v_mfma_f32_16x16x32_bf16 v[52:55], v[144:147], v[186:189], v[52:55]
	v_mfma_f32_16x16x32_bf16 v[52:55], v[148:151], v[190:193], v[52:55]
	v_mfma_f32_16x16x32_bf16 v[48:51], v[178:181], v[186:189], v[48:51]
	v_mfma_f32_16x16x32_bf16 v[48:51], v[182:185], v[190:193], v[48:51]
	v_mfma_f32_16x16x32_bf16 v[36:39], v[144:147], v[194:197], v[36:39]
	v_mfma_f32_16x16x32_bf16 v[36:39], v[148:151], v[198:201], v[36:39]
	v_mfma_f32_16x16x32_bf16 v[32:35], v[178:181], v[194:197], v[32:35]
	v_mfma_f32_16x16x32_bf16 v[32:35], v[182:185], v[198:201], v[32:35]
	v_mfma_f32_16x16x32_bf16 v[20:23], v[144:147], v[202:205], v[20:23]
	v_mfma_f32_16x16x32_bf16 v[20:23], v[148:151], v[206:209], v[20:23]
	v_mfma_f32_16x16x32_bf16 v[16:19], v[178:181], v[202:205], v[16:19]
	v_mfma_f32_16x16x32_bf16 v[16:19], v[182:185], v[206:209], v[16:19]
	v_mfma_f32_16x16x32_bf16 v[4:7], v[144:147], v[210:213], v[4:7]
	v_mfma_f32_16x16x32_bf16 v[4:7], v[148:151], v[214:217], v[4:7]
	v_mfma_f32_16x16x32_bf16 v[0:3], v[178:181], v[210:213], v[0:3]
	v_mfma_f32_16x16x32_bf16 v[0:3], v[182:185], v[214:217], v[0:3]
	s_setprio 2
	s_barrier
	s_add_i32 s64, 0, 0x18000
	s_add_i32 s65, 0, 0x1c000
	v_add_u32_e32 v140, s64, v174
	v_add_u32_e32 v161, s65, v174
	ds_read_b128 v[128:131], v140
	ds_read_b128 v[132:135], v140 offset:1024
	ds_read_b128 v[136:139], v140 offset:2048
	ds_read_b128 v[140:143], v140 offset:3072
	ds_read_b128 v[144:147], v161
	ds_read_b128 v[148:151], v161 offset:1024
	ds_read_b128 v[178:181], v161 offset:2048
	ds_read_b128 v[182:185], v161 offset:3072
	s_add_u32 s42, s42, 0x4000
	s_addc_u32 s43, s43, 0
	s_mov_b32 m0, s23
	v_lshl_add_u64 v[172:173], s[42:43], 0, v[158:159]
	ds_read_b128 v[186:189], v177 offset:32768
	ds_read_b128 v[190:193], v177 offset:33792
	ds_read_b128 v[194:197], v177 offset:34816
	ds_read_b128 v[198:201], v177 offset:35840
	ds_read_b128 v[202:205], v177 offset:36864
	ds_read_b128 v[206:209], v177 offset:37888
	ds_read_b128 v[210:213], v177 offset:38912
	ds_read_b128 v[214:217], v177 offset:39936
	global_load_lds_dwordx4 v[172:173], off
	v_lshl_add_u64 v[172:173], s[42:43], 0, v[154:155]
	s_mov_b32 m0, s24
	s_nop 0
	global_load_lds_dwordx4 v[172:173], off
	s_waitcnt vmcnt(8)
	s_waitcnt lgkmcnt(0)
	s_barrier
	s_setprio 1
	s_waitcnt lgkmcnt(0)
	v_mfma_f32_16x16x32_bf16 v[124:127], v[128:131], v[186:189], v[124:127]
	v_mfma_f32_16x16x32_bf16 v[124:127], v[132:135], v[190:193], v[124:127]
	v_mfma_f32_16x16x32_bf16 v[120:123], v[136:139], v[186:189], v[120:123]
	v_mfma_f32_16x16x32_bf16 v[120:123], v[140:143], v[190:193], v[120:123]
	v_mfma_f32_16x16x32_bf16 v[108:111], v[128:131], v[194:197], v[108:111]
	v_mfma_f32_16x16x32_bf16 v[108:111], v[132:135], v[198:201], v[108:111]
	v_mfma_f32_16x16x32_bf16 v[104:107], v[136:139], v[194:197], v[104:107]
	v_mfma_f32_16x16x32_bf16 v[104:107], v[140:143], v[198:201], v[104:107]
	v_mfma_f32_16x16x32_bf16 v[92:95], v[128:131], v[202:205], v[92:95]
	v_mfma_f32_16x16x32_bf16 v[92:95], v[132:135], v[206:209], v[92:95]
	v_mfma_f32_16x16x32_bf16 v[88:91], v[136:139], v[202:205], v[88:91]
	v_mfma_f32_16x16x32_bf16 v[88:91], v[140:143], v[206:209], v[88:91]
	v_mfma_f32_16x16x32_bf16 v[76:79], v[128:131], v[210:213], v[76:79]
	v_mfma_f32_16x16x32_bf16 v[76:79], v[132:135], v[214:217], v[76:79]
	v_mfma_f32_16x16x32_bf16 v[72:75], v[136:139], v[210:213], v[72:75]
	v_mfma_f32_16x16x32_bf16 v[72:75], v[140:143], v[214:217], v[72:75]
	s_setprio 0
	s_setprio 1
	v_mfma_f32_16x16x32_bf16 v[116:119], v[144:147], v[186:189], v[116:119]
	v_mfma_f32_16x16x32_bf16 v[116:119], v[148:151], v[190:193], v[116:119]
	v_mfma_f32_16x16x32_bf16 v[112:115], v[178:181], v[186:189], v[112:115]
	v_mfma_f32_16x16x32_bf16 v[112:115], v[182:185], v[190:193], v[112:115]
	v_mfma_f32_16x16x32_bf16 v[100:103], v[144:147], v[194:197], v[100:103]
	v_mfma_f32_16x16x32_bf16 v[100:103], v[148:151], v[198:201], v[100:103]
	v_mfma_f32_16x16x32_bf16 v[96:99], v[178:181], v[194:197], v[96:99]
	v_mfma_f32_16x16x32_bf16 v[96:99], v[182:185], v[198:201], v[96:99]
	v_mfma_f32_16x16x32_bf16 v[84:87], v[144:147], v[202:205], v[84:87]
	v_mfma_f32_16x16x32_bf16 v[84:87], v[148:151], v[206:209], v[84:87]
	v_mfma_f32_16x16x32_bf16 v[80:83], v[178:181], v[202:205], v[80:83]
	v_mfma_f32_16x16x32_bf16 v[80:83], v[182:185], v[206:209], v[80:83]
	v_mfma_f32_16x16x32_bf16 v[68:71], v[144:147], v[210:213], v[68:71]
	v_mfma_f32_16x16x32_bf16 v[68:71], v[148:151], v[214:217], v[68:71]
	v_mfma_f32_16x16x32_bf16 v[64:67], v[178:181], v[210:213], v[64:67]
	v_mfma_f32_16x16x32_bf16 v[64:67], v[182:185], v[214:217], v[64:67]
	s_setprio 2
	s_barrier
; #define PG8_STAGE(bufoff, gbase, voff) do { _Pragma("unroll") for (int _i = 0; _i < 2; ++_i) \
;         __builtin_amdgcn_global_load_lds((const unsigned*)((const char*)(gbase) + (voff)[_i]), (PG8_LAS unsigned*)(lds + (bufoff) + ldsw + _i * 8192), 16, 0, 0); } while (0)
; #define PG8_LDA(dst, b, h) do { _Pragma("unroll") for (int m = 0; m < 4; ++m) _Pragma("unroll") for (int k = 0; k < 2; ++k) dst[m][k] = *(const PG8_LAS bf16x8*)(lds + PG8_SA(b, h) + aoff + m * 2048 + k * 1024); } while (0)
; #define PG8_MMA(ai, bj, At, Bt) do { __builtin_amdgcn_s_setprio(1); _Pragma("unroll") for (int m = 0; m < 4; ++m) _Pragma("unroll") for (int n = 0; n < 2; ++n) _Pragma("unroll") for (int k = 0; k < 2; ++k) \
;         acc[ai][bj][m][n] = __builtin_amdgcn_mfma_f32_16x16x32_bf16(Bt[n][k], At[m][k], acc[ai][bj][m][n], 0, 0, 0); __builtin_amdgcn_s_setprio(0); } while (0)
; #define PG8_WAIT_V(n) asm volatile("s_waitcnt vmcnt(" #n ")" ::: "memory")
; #define PG8_WAIT_L(n) asm volatile("s_waitcnt lgkmcnt(" #n ")" ::: "memory")
; #define PG8_BAR __builtin_amdgcn_s_barrier()
; #define PG8_SCHED __builtin_amdgcn_sched_barrier(0)
; template <class Epi, class Sched, bool ALIGN_EPI = false, bool SP2 = false>
; __device__ __forceinline__ void gemm_phase(PG8_LAS unsigned char* lds, const Gemm g, const Sched& S, const Epi& E) {
;     ...
;             PG8_LDA(At, 1, 1); PG8_STAGE(PG8_SB(1, 0), b3, voffB); PG8_STAGE(PG8_SB(1, 1), b3 + hstepB, voffB); PG8_STAGE(PG8_SA(1, 0), a3, voffA);
;             PG8_WAIT_V(8); PG8_WAIT_L(0); PG8_BAR; PG8_MMA(1, 0, At, B0); PG8_MMA(1, 1, At, B1); PG8_BAR; PG8_SCHED;
;     ...
;         if constexpr (ALIGN_EPI) { if (wr == 0) PG8_BAR; }
	s_add_u32 s42, s40, 0x8000
	s_addc_u32 s43, s41, 0
	s_add_i32 s64, s64, s20
	v_lshl_add_u64 v[172:173], s[42:43], 0, v[156:157]
	s_mov_b32 m0, s64
	ds_read_b128 v[186:189], v177 offset:49152
	ds_read_b128 v[190:193], v177 offset:50176
	ds_read_b128 v[194:197], v177 offset:51200
	ds_read_b128 v[198:201], v177 offset:52224
	ds_read_b128 v[202:205], v177 offset:53248
	ds_read_b128 v[206:209], v177 offset:54272
	ds_read_b128 v[210:213], v177 offset:55296
	ds_read_b128 v[214:217], v177 offset:56320
	global_load_lds_dwordx4 v[172:173], off
	s_add_i32 m0, s64, 0x2000
	s_add_u32 s40, s40, 0xc000
	v_lshl_add_u64 v[172:173], s[42:43], 0, v[152:153]
	s_addc_u32 s41, s41, 0
	s_add_i32 s42, s65, s20
	global_load_lds_dwordx4 v[172:173], off
	v_lshl_add_u64 v[172:173], s[40:41], 0, v[156:157]
	s_mov_b32 m0, s42
	s_nop 0
	global_load_lds_dwordx4 v[172:173], off
	v_lshl_add_u64 v[172:173], s[40:41], 0, v[152:153]
	s_add_i32 m0, s42, 0x2000
	s_nop 0
	global_load_lds_dwordx4 v[172:173], off
	v_lshl_add_u64 v[172:173], s[38:39], 0, v[158:159]
	s_mov_b32 m0, s29
	s_nop 0
	global_load_lds_dwordx4 v[172:173], off
	v_lshl_add_u64 v[172:173], s[38:39], 0, v[154:155]
	s_mov_b32 m0, s30
	s_nop 0
	global_load_lds_dwordx4 v[172:173], off
	s_waitcnt vmcnt(8)
	s_waitcnt lgkmcnt(0)
	s_barrier
	s_setprio 1
	s_waitcnt lgkmcnt(0)
	v_mfma_f32_16x16x32_bf16 v[60:63], v[128:131], v[186:189], v[60:63]
	v_mfma_f32_16x16x32_bf16 v[60:63], v[132:135], v[190:193], v[60:63]
	v_mfma_f32_16x16x32_bf16 v[56:59], v[136:139], v[186:189], v[56:59]
	v_mfma_f32_16x16x32_bf16 v[56:59], v[140:143], v[190:193], v[56:59]
	v_mfma_f32_16x16x32_bf16 v[44:47], v[128:131], v[194:197], v[44:47]
	v_mfma_f32_16x16x32_bf16 v[44:47], v[132:135], v[198:201], v[44:47]
	v_mfma_f32_16x16x32_bf16 v[40:43], v[136:139], v[194:197], v[40:43]
	v_mfma_f32_16x16x32_bf16 v[40:43], v[140:143], v[198:201], v[40:43]
	v_mfma_f32_16x16x32_bf16 v[28:31], v[128:131], v[202:205], v[28:31]
	v_mfma_f32_16x16x32_bf16 v[28:31], v[132:135], v[206:209], v[28:31]
	v_mfma_f32_16x16x32_bf16 v[24:27], v[136:139], v[202:205], v[24:27]
	v_mfma_f32_16x16x32_bf16 v[24:27], v[140:143], v[206:209], v[24:27]
	v_mfma_f32_16x16x32_bf16 v[12:15], v[128:131], v[210:213], v[12:15]
	v_mfma_f32_16x16x32_bf16 v[12:15], v[132:135], v[214:217], v[12:15]
	v_mfma_f32_16x16x32_bf16 v[8:11], v[136:139], v[210:213], v[8:11]
	v_mfma_f32_16x16x32_bf16 v[8:11], v[140:143], v[214:217], v[8:11]
	s_setprio 0
	s_setprio 1
	v_mfma_f32_16x16x32_bf16 v[52:55], v[144:147], v[186:189], v[52:55]
	v_mfma_f32_16x16x32_bf16 v[52:55], v[148:151], v[190:193], v[52:55]
	v_mfma_f32_16x16x32_bf16 v[48:51], v[178:181], v[186:189], v[48:51]
	v_mfma_f32_16x16x32_bf16 v[48:51], v[182:185], v[190:193], v[48:51]
	v_mfma_f32_16x16x32_bf16 v[36:39], v[144:147], v[194:197], v[36:39]
	v_mfma_f32_16x16x32_bf16 v[36:39], v[148:151], v[198:201], v[36:39]
	v_mfma_f32_16x16x32_bf16 v[32:35], v[178:181], v[194:197], v[32:35]
	v_mfma_f32_16x16x32_bf16 v[32:35], v[182:185], v[198:201], v[32:35]
	v_mfma_f32_16x16x32_bf16 v[20:23], v[144:147], v[202:205], v[20:23]
	v_mfma_f32_16x16x32_bf16 v[20:23], v[148:151], v[206:209], v[20:23]
	v_mfma_f32_16x16x32_bf16 v[16:19], v[178:181], v[202:205], v[16:19]
	v_mfma_f32_16x16x32_bf16 v[16:19], v[182:185], v[206:209], v[16:19]
	v_mfma_f32_16x16x32_bf16 v[4:7], v[144:147], v[210:213], v[4:7]
	v_mfma_f32_16x16x32_bf16 v[4:7], v[148:151], v[214:217], v[4:7]
	v_mfma_f32_16x16x32_bf16 v[0:3], v[178:181], v[210:213], v[0:3]
	v_mfma_f32_16x16x32_bf16 v[0:3], v[182:185], v[214:217], v[0:3]
	s_setprio 2
	s_barrier
	s_add_u32 s36, s36, 0x10000
	s_addc_u32 s37, s37, 0
	s_add_u32 s78, s78, 0x10000
	s_addc_u32 s82, s82, 0
	s_cmp_ge_u32 s84, s26
	s_mov_b32 s38, s84
	s_cbranch_scc0 .LBB0_193
	s_and_b64 vcc, exec, s[60:61]
	s_cbranch_vccz .LBB0_196
	s_barrier

; #define PG8_STAGE(bufoff, gbase, voff) do { _Pragma("unroll") for (int _i = 0; _i < 2; ++_i) \
;         __builtin_amdgcn_global_load_lds((const unsigned*)((const char*)(gbase) + (voff)[_i]), (PG8_LAS unsigned*)(lds + (bufoff) + ldsw + _i * 8192), 16, 0, 0); } while (0)
; #define PG8_LDA(dst, b, h) do { _Pragma("unroll") for (int m = 0; m < 4; ++m) _Pragma("unroll") for (int k = 0; k < 2; ++k) dst[m][k] = *(const PG8_LAS bf16x8*)(lds + PG8_SA(b, h) + aoff + m * 2048 + k * 1024); } while (0)
; #define PG8_LDB(dst, b, h) do { _Pragma("unroll") for (int n = 0; n < 2; ++n) _Pragma("unroll") for (int k = 0; k < 2; ++k) dst[n][k] = *(const PG8_LAS bf16x8*)(lds + PG8_SB(b, h) + boff + n * 2048 + k * 1024); } while (0)
; #define PG8_MMA(ai, bj, At, Bt) do { __builtin_amdgcn_s_setprio(1); _Pragma("unroll") for (int m = 0; m < 4; ++m) _Pragma("unroll") for (int n = 0; n < 2; ++n) _Pragma("unroll") for (int k = 0; k < 2; ++k) \
;         acc[ai][bj][m][n] = __builtin_amdgcn_mfma_f32_16x16x32_bf16(Bt[n][k], At[m][k], acc[ai][bj][m][n], 0, 0, 0); __builtin_amdgcn_s_setprio(0); } while (0)
; #define PG8_WAIT_V(n) asm volatile("s_waitcnt vmcnt(" #n ")" ::: "memory")
; #define PG8_WAIT_L(n) asm volatile("s_waitcnt lgkmcnt(" #n ")" ::: "memory")
; #define PG8_BAR __builtin_amdgcn_s_barrier()
; #define PG8_SCHED __builtin_amdgcn_sched_barrier(0)
; template <class Epi, class Sched, bool ALIGN_EPI = false, bool SP2 = false>
; __device__ __forceinline__ void gemm_phase(PG8_LAS unsigned char* lds, const Gemm g, const Sched& S, const Epi& E) {
;     ...
;             const bool last = (t == nt - 2);
;             const char* a1 = cA + (size_t)(t + 1) * kstepB;
;             const char* a2 = last ? nA : cA + (size_t)(t + 2) * kstepB; const char* b2 = last ? nB : cB + (size_t)(t + 2) * kstepB;
;             const char* a3 = a2 + kstepB; const char* b3 = b2 + kstepB;
;             if (last && has_next) S.a_ready(nxt);
;             if constexpr (SP2) {
;             PG8_LDB(B0, 0, 0); PG8_LDB(B1, 0, 1); PG8_SCHED; PG8_LDA(At, 0, 0); PG8_STAGE(PG8_SA(1, 1), a1 + hstepB, voffA);
;             PG8_WAIT_V(8); PG8_WAIT_L(0); PG8_BAR; PG8_MMA(0, 0, At, B0); PG8_MMA(0, 1, At, B1); PG8_BAR; PG8_SCHED;
;             PG8_LDA(At, 0, 1); PG8_STAGE(PG8_SB(0, 0), b2, voffB); PG8_STAGE(PG8_SB(0, 1), b2 + hstepB, voffB); PG8_STAGE(PG8_SA(0, 0), a2, voffA);
.LBB0_232:
	s_add_u32 s31, s36, 0x4000
	s_addc_u32 s38, s37, 0
	s_cmp_eq_u32 s30, 28
	s_cselect_b32 s42, s26, s31
	s_cselect_b32 s43, s13, s38
	s_cselect_b32 s40, s27, s28
	s_cselect_b32 s41, s11, s29
	s_add_u32 s38, s42, 0x8000
	s_addc_u32 s39, s43, 0
	s_add_i32 s31, 0, 0x10000
	s_add_i32 s60, 0, 0x14000
	v_add_u32_e32 v152, s31, v169
	v_add_u32_e32 v175, s60, v169
	ds_read_b128 v[128:131], v152
	ds_read_b128 v[132:135], v152 offset:1024
	ds_read_b128 v[148:151], v152 offset:2048
	ds_read_b128 v[152:155], v152 offset:3072
	ds_read_b128 v[156:159], v175
	ds_read_b128 v[160:163], v175 offset:1024
	ds_read_b128 v[164:167], v175 offset:2048
	ds_read_b128 v[176:179], v175 offset:3072
	v_lshl_add_u64 v[212:213], s[36:37], 0, v[144:145]
	s_add_i32 m0, s17, 0xc000
	ds_read_b128 v[180:183], v174
	ds_read_b128 v[184:187], v174 offset:1024
	ds_read_b128 v[188:191], v174 offset:2048
	ds_read_b128 v[192:195], v174 offset:3072
	ds_read_b128 v[196:199], v174 offset:4096
	ds_read_b128 v[200:203], v174 offset:5120
	ds_read_b128 v[204:207], v174 offset:6144
	ds_read_b128 v[208:211], v174 offset:7168
	global_load_lds_dwordx4 v[212:213], off
	v_lshl_add_u64 v[212:213], s[36:37], 0, v[146:147]
	s_add_i32 m0, s17, 0xe000
	s_nop 0
	global_load_lds_dwordx4 v[212:213], off
	s_waitcnt vmcnt(8)
	s_waitcnt lgkmcnt(0)
	s_barrier
	s_setprio 1
	s_waitcnt lgkmcnt(0)
	v_mfma_f32_16x16x32_bf16 v[124:127], v[128:131], v[180:183], v[124:127]
	v_mfma_f32_16x16x32_bf16 v[124:127], v[132:135], v[184:187], v[124:127]
	v_mfma_f32_16x16x32_bf16 v[120:123], v[148:151], v[180:183], v[120:123]
	v_mfma_f32_16x16x32_bf16 v[120:123], v[152:155], v[184:187], v[120:123]
	v_mfma_f32_16x16x32_bf16 v[108:111], v[128:131], v[188:191], v[108:111]
	v_mfma_f32_16x16x32_bf16 v[108:111], v[132:135], v[192:195], v[108:111]
	v_mfma_f32_16x16x32_bf16 v[104:107], v[148:151], v[188:191], v[104:107]
	v_mfma_f32_16x16x32_bf16 v[104:107], v[152:155], v[192:195], v[104:107]
	v_mfma_f32_16x16x32_bf16 v[92:95], v[128:131], v[196:199], v[92:95]
	v_mfma_f32_16x16x32_bf16 v[92:95], v[132:135], v[200:203], v[92:95]
	v_mfma_f32_16x16x32_bf16 v[88:91], v[148:151], v[196:199], v[88:91]
	v_mfma_f32_16x16x32_bf16 v[88:91], v[152:155], v[200:203], v[88:91]
	v_mfma_f32_16x16x32_bf16 v[76:79], v[128:131], v[204:207], v[76:79]
	v_mfma_f32_16x16x32_bf16 v[76:79], v[132:135], v[208:211], v[76:79]
	v_mfma_f32_16x16x32_bf16 v[72:75], v[148:151], v[204:207], v[72:75]
	v_mfma_f32_16x16x32_bf16 v[72:75], v[152:155], v[208:211], v[72:75]
	s_setprio 0
	s_setprio 1
	v_mfma_f32_16x16x32_bf16 v[116:119], v[156:159], v[180:183], v[116:119]
	v_mfma_f32_16x16x32_bf16 v[116:119], v[160:163], v[184:187], v[116:119]
	v_mfma_f32_16x16x32_bf16 v[112:115], v[164:167], v[180:183], v[112:115]
	v_mfma_f32_16x16x32_bf16 v[112:115], v[176:179], v[184:187], v[112:115]
	v_mfma_f32_16x16x32_bf16 v[100:103], v[156:159], v[188:191], v[100:103]
	v_mfma_f32_16x16x32_bf16 v[100:103], v[160:163], v[192:195], v[100:103]
	v_mfma_f32_16x16x32_bf16 v[96:99], v[164:167], v[188:191], v[96:99]
	v_mfma_f32_16x16x32_bf16 v[96:99], v[176:179], v[192:195], v[96:99]
	v_mfma_f32_16x16x32_bf16 v[84:87], v[156:159], v[196:199], v[84:87]
	v_mfma_f32_16x16x32_bf16 v[84:87], v[160:163], v[200:203], v[84:87]
	v_mfma_f32_16x16x32_bf16 v[80:83], v[164:167], v[196:199], v[80:83]
	v_mfma_f32_16x16x32_bf16 v[80:83], v[176:179], v[200:203], v[80:83]
	v_mfma_f32_16x16x32_bf16 v[68:71], v[156:159], v[204:207], v[68:71]
	v_mfma_f32_16x16x32_bf16 v[68:71], v[160:163], v[208:211], v[68:71]
	v_mfma_f32_16x16x32_bf16 v[64:67], v[164:167], v[204:207], v[64:67]
	v_mfma_f32_16x16x32_bf16 v[64:67], v[176:179], v[208:211], v[64:67]
	s_setprio 2
	s_barrier
	s_add_i32 s31, s31, s14
	v_lshl_add_u64 v[212:213], s[40:41], 0, v[220:221]
	s_mov_b32 m0, s31
	ds_read_b128 v[180:183], v174 offset:16384
	ds_read_b128 v[184:187], v174 offset:17408
	ds_read_b128 v[188:191], v174 offset:18432
	ds_read_b128 v[192:195], v174 offset:19456
	ds_read_b128 v[196:199], v174 offset:20480
	ds_read_b128 v[200:203], v174 offset:21504
	ds_read_b128 v[204:207], v174 offset:22528
	ds_read_b128 v[208:211], v174 offset:23552
	global_load_lds_dwordx4 v[212:213], off
	s_add_i32 m0, s31, 0x2000
	s_add_u32 s44, s40, 0x4000
	v_lshl_add_u64 v[212:213], s[40:41], 0, v[136:137]
	s_addc_u32 s45, s41, 0
	s_add_i32 s31, s60, s14
	global_load_lds_dwordx4 v[212:213], off
	v_lshl_add_u64 v[212:213], s[44:45], 0, v[220:221]
	s_mov_b32 m0, s31
	s_nop 0
	global_load_lds_dwordx4 v[212:213], off
	v_lshl_add_u64 v[212:213], s[44:45], 0, v[136:137]
	s_add_i32 m0, s31, 0x2000
	s_nop 0
	global_load_lds_dwordx4 v[212:213], off
	v_lshl_add_u64 v[212:213], s[42:43], 0, v[140:141]
	s_mov_b32 m0, s17
	s_nop 0
	global_load_lds_dwordx4 v[212:213], off
	v_lshl_add_u64 v[212:213], s[42:43], 0, v[138:139]
	s_mov_b32 m0, s18
	s_nop 0
	global_load_lds_dwordx4 v[212:213], off
	s_waitcnt vmcnt(8)
	s_waitcnt lgkmcnt(0)
	s_barrier
; #define PG8_STAGE(bufoff, gbase, voff) do { _Pragma("unroll") for (int _i = 0; _i < 2; ++_i) \
;         __builtin_amdgcn_global_load_lds((const unsigned*)((const char*)(gbase) + (voff)[_i]), (PG8_LAS unsigned*)(lds + (bufoff) + ldsw + _i * 8192), 16, 0, 0); } while (0)
; #define PG8_LDA(dst, b, h) do { _Pragma("unroll") for (int m = 0; m < 4; ++m) _Pragma("unroll") for (int k = 0; k < 2; ++k) dst[m][k] = *(const PG8_LAS bf16x8*)(lds + PG8_SA(b, h) + aoff + m * 2048 + k * 1024); } while (0)
; #define PG8_LDB(dst, b, h) do { _Pragma("unroll") for (int n = 0; n < 2; ++n) _Pragma("unroll") for (int k = 0; k < 2; ++k) dst[n][k] = *(const PG8_LAS bf16x8*)(lds + PG8_SB(b, h) + boff + n * 2048 + k * 1024); } while (0)
; #define PG8_MMA(ai, bj, At, Bt) do { __builtin_amdgcn_s_setprio(1); _Pragma("unroll") for (int m = 0; m < 4; ++m) _Pragma("unroll") for (int n = 0; n < 2; ++n) _Pragma("unroll") for (int k = 0; k < 2; ++k) \
;         acc[ai][bj][m][n] = __builtin_amdgcn_mfma_f32_16x16x32_bf16(Bt[n][k], At[m][k], acc[ai][bj][m][n], 0, 0, 0); __builtin_amdgcn_s_setprio(0); } while (0)
; #define PG8_WAIT_V(n) asm volatile("s_waitcnt vmcnt(" #n ")" ::: "memory")
; #define PG8_WAIT_L(n) asm volatile("s_waitcnt lgkmcnt(" #n ")" ::: "memory")
; #define PG8_BAR __builtin_amdgcn_s_barrier()
; #define PG8_SCHED __builtin_amdgcn_sched_barrier(0)
; template <class Epi, class Sched, bool ALIGN_EPI = false, bool SP2 = false>
; __device__ __forceinline__ void gemm_phase(PG8_LAS unsigned char* lds, const Gemm g, const Sched& S, const Epi& E) {
;     ...
;             PG8_WAIT_V(8); PG8_WAIT_L(0); PG8_BAR; PG8_MMA(1, 0, At, B0); PG8_MMA(1, 1, At, B1); PG8_BAR; PG8_SCHED;
;             PG8_LDB(B0, 1, 0); PG8_LDB(B1, 1, 1); PG8_SCHED; PG8_LDA(At, 1, 0); PG8_STAGE(PG8_SA(0, 1), a2 + hstepB, voffA);
;             PG8_WAIT_V(8); PG8_WAIT_L(0); PG8_BAR; PG8_MMA(0, 0, At, B0); PG8_MMA(0, 1, At, B1); PG8_BAR; PG8_SCHED;
	s_setprio 1
	s_waitcnt lgkmcnt(0)
	v_mfma_f32_16x16x32_bf16 v[60:63], v[128:131], v[180:183], v[60:63]
	v_mfma_f32_16x16x32_bf16 v[60:63], v[132:135], v[184:187], v[60:63]
	v_mfma_f32_16x16x32_bf16 v[56:59], v[148:151], v[180:183], v[56:59]
	v_mfma_f32_16x16x32_bf16 v[56:59], v[152:155], v[184:187], v[56:59]
	v_mfma_f32_16x16x32_bf16 v[48:51], v[128:131], v[188:191], v[48:51]
	v_mfma_f32_16x16x32_bf16 v[48:51], v[132:135], v[192:195], v[48:51]
	v_mfma_f32_16x16x32_bf16 v[40:43], v[148:151], v[188:191], v[40:43]
	v_mfma_f32_16x16x32_bf16 v[40:43], v[152:155], v[192:195], v[40:43]
	v_mfma_f32_16x16x32_bf16 v[32:35], v[128:131], v[196:199], v[32:35]
	v_mfma_f32_16x16x32_bf16 v[32:35], v[132:135], v[200:203], v[32:35]
	v_mfma_f32_16x16x32_bf16 v[24:27], v[148:151], v[196:199], v[24:27]
	v_mfma_f32_16x16x32_bf16 v[24:27], v[152:155], v[200:203], v[24:27]
	v_mfma_f32_16x16x32_bf16 v[16:19], v[128:131], v[204:207], v[16:19]
	v_mfma_f32_16x16x32_bf16 v[16:19], v[132:135], v[208:211], v[16:19]
	v_mfma_f32_16x16x32_bf16 v[8:11], v[148:151], v[204:207], v[8:11]
	v_mfma_f32_16x16x32_bf16 v[8:11], v[152:155], v[208:211], v[8:11]
	s_setprio 0
	s_setprio 1
	v_mfma_f32_16x16x32_bf16 v[52:55], v[156:159], v[180:183], v[52:55]
	v_mfma_f32_16x16x32_bf16 v[52:55], v[160:163], v[184:187], v[52:55]
	v_mfma_f32_16x16x32_bf16 v[44:47], v[164:167], v[180:183], v[44:47]
	v_mfma_f32_16x16x32_bf16 v[44:47], v[176:179], v[184:187], v[44:47]
	v_mfma_f32_16x16x32_bf16 v[36:39], v[156:159], v[188:191], v[36:39]
	v_mfma_f32_16x16x32_bf16 v[36:39], v[160:163], v[192:195], v[36:39]
	v_mfma_f32_16x16x32_bf16 v[28:31], v[164:167], v[188:191], v[28:31]
	v_mfma_f32_16x16x32_bf16 v[28:31], v[176:179], v[192:195], v[28:31]
	v_mfma_f32_16x16x32_bf16 v[20:23], v[156:159], v[196:199], v[20:23]
	v_mfma_f32_16x16x32_bf16 v[20:23], v[160:163], v[200:203], v[20:23]
	v_mfma_f32_16x16x32_bf16 v[12:15], v[164:167], v[196:199], v[12:15]
	v_mfma_f32_16x16x32_bf16 v[12:15], v[176:179], v[200:203], v[12:15]
	v_mfma_f32_16x16x32_bf16 v[4:7], v[156:159], v[204:207], v[4:7]
	v_mfma_f32_16x16x32_bf16 v[4:7], v[160:163], v[208:211], v[4:7]
	v_mfma_f32_16x16x32_bf16 v[0:3], v[164:167], v[204:207], v[0:3]
	v_mfma_f32_16x16x32_bf16 v[0:3], v[176:179], v[208:211], v[0:3]
	s_setprio 2
	s_barrier
	s_add_i32 s31, 0, 0x18000
	s_add_i32 s44, 0, 0x1c000
	v_add_u32_e32 v152, s31, v169
	v_add_u32_e32 v175, s44, v169
	ds_read_b128 v[128:131], v152
	ds_read_b128 v[132:135], v152 offset:1024
	ds_read_b128 v[148:151], v152 offset:2048
	ds_read_b128 v[152:155], v152 offset:3072
	ds_read_b128 v[156:159], v175
	ds_read_b128 v[160:163], v175 offset:1024
	ds_read_b128 v[164:167], v175 offset:2048
	ds_read_b128 v[176:179], v175 offset:3072
	s_add_u32 s42, s42, 0x4000
	s_addc_u32 s43, s43, 0
	s_mov_b32 m0, s19
	v_lshl_add_u64 v[212:213], s[42:43], 0, v[140:141]
	ds_read_b128 v[180:183], v174 offset:32768
	ds_read_b128 v[184:187], v174 offset:33792
	ds_read_b128 v[188:191], v174 offset:34816
	ds_read_b128 v[192:195], v174 offset:35840
	ds_read_b128 v[196:199], v174 offset:36864
	ds_read_b128 v[200:203], v174 offset:37888
	ds_read_b128 v[204:207], v174 offset:38912
	ds_read_b128 v[208:211], v174 offset:39936
	global_load_lds_dwordx4 v[212:213], off
	v_lshl_add_u64 v[212:213], s[42:43], 0, v[138:139]
	s_mov_b32 m0, s20
	s_nop 0
	global_load_lds_dwordx4 v[212:213], off
	s_waitcnt vmcnt(8)
	s_waitcnt lgkmcnt(0)
	s_barrier
	s_setprio 1
	s_waitcnt lgkmcnt(0)
	v_mfma_f32_16x16x32_bf16 v[124:127], v[128:131], v[180:183], v[124:127]
	v_mfma_f32_16x16x32_bf16 v[124:127], v[132:135], v[184:187], v[124:127]
	v_mfma_f32_16x16x32_bf16 v[120:123], v[148:151], v[180:183], v[120:123]
	v_mfma_f32_16x16x32_bf16 v[120:123], v[152:155], v[184:187], v[120:123]
	v_mfma_f32_16x16x32_bf16 v[108:111], v[128:131], v[188:191], v[108:111]
	v_mfma_f32_16x16x32_bf16 v[108:111], v[132:135], v[192:195], v[108:111]
	v_mfma_f32_16x16x32_bf16 v[104:107], v[148:151], v[188:191], v[104:107]
	v_mfma_f32_16x16x32_bf16 v[104:107], v[152:155], v[192:195], v[104:107]
	v_mfma_f32_16x16x32_bf16 v[92:95], v[128:131], v[196:199], v[92:95]
	v_mfma_f32_16x16x32_bf16 v[92:95], v[132:135], v[200:203], v[92:95]
	v_mfma_f32_16x16x32_bf16 v[88:91], v[148:151], v[196:199], v[88:91]
	v_mfma_f32_16x16x32_bf16 v[88:91], v[152:155], v[200:203], v[88:91]
	v_mfma_f32_16x16x32_bf16 v[76:79], v[128:131], v[204:207], v[76:79]
	v_mfma_f32_16x16x32_bf16 v[76:79], v[132:135], v[208:211], v[76:79]
	v_mfma_f32_16x16x32_bf16 v[72:75], v[148:151], v[204:207], v[72:75]
	v_mfma_f32_16x16x32_bf16 v[72:75], v[152:155], v[208:211], v[72:75]
	s_setprio 0
	s_setprio 1
	v_mfma_f32_16x16x32_bf16 v[116:119], v[156:159], v[180:183], v[116:119]
	v_mfma_f32_16x16x32_bf16 v[116:119], v[160:163], v[184:187], v[116:119]
	v_mfma_f32_16x16x32_bf16 v[112:115], v[164:167], v[180:183], v[112:115]
	v_mfma_f32_16x16x32_bf16 v[112:115], v[176:179], v[184:187], v[112:115]
	v_mfma_f32_16x16x32_bf16 v[100:103], v[156:159], v[188:191], v[100:103]
	v_mfma_f32_16x16x32_bf16 v[100:103], v[160:163], v[192:195], v[100:103]
	v_mfma_f32_16x16x32_bf16 v[96:99], v[164:167], v[188:191], v[96:99]
	v_mfma_f32_16x16x32_bf16 v[96:99], v[176:179], v[192:195], v[96:99]
	v_mfma_f32_16x16x32_bf16 v[84:87], v[156:159], v[196:199], v[84:87]
	v_mfma_f32_16x16x32_bf16 v[84:87], v[160:163], v[200:203], v[84:87]
	v_mfma_f32_16x16x32_bf16 v[80:83], v[164:167], v[196:199], v[80:83]
	v_mfma_f32_16x16x32_bf16 v[80:83], v[176:179], v[200:203], v[80:83]
	v_mfma_f32_16x16x32_bf16 v[68:71], v[156:159], v[204:207], v[68:71]
	v_mfma_f32_16x16x32_bf16 v[68:71], v[160:163], v[208:211], v[68:71]
	v_mfma_f32_16x16x32_bf16 v[64:67], v[164:167], v[204:207], v[64:67]
	v_mfma_f32_16x16x32_bf16 v[64:67], v[176:179], v[208:211], v[64:67]
	s_setprio 2
	s_barrier
; #define PG8_STAGE(bufoff, gbase, voff) do { _Pragma("unroll") for (int _i = 0; _i < 2; ++_i) \
;         __builtin_amdgcn_global_load_lds((const unsigned*)((const char*)(gbase) + (voff)[_i]), (PG8_LAS unsigned*)(lds + (bufoff) + ldsw + _i * 8192), 16, 0, 0); } while (0)
; #define PG8_LDA(dst, b, h) do { _Pragma("unroll") for (int m = 0; m < 4; ++m) _Pragma("unroll") for (int k = 0; k < 2; ++k) dst[m][k] = *(const PG8_LAS bf16x8*)(lds + PG8_SA(b, h) + aoff + m * 2048 + k * 1024); } while (0)
; #define PG8_MMA(ai, bj, At, Bt) do { __builtin_amdgcn_s_setprio(1); _Pragma("unroll") for (int m = 0; m < 4; ++m) _Pragma("unroll") for (int n = 0; n < 2; ++n) _Pragma("unroll") for (int k = 0; k < 2; ++k) \
;         acc[ai][bj][m][n] = __builtin_amdgcn_mfma_f32_16x16x32_bf16(Bt[n][k], At[m][k], acc[ai][bj][m][n], 0, 0, 0); __builtin_amdgcn_s_setprio(0); } while (0)
; #define PG8_WAIT_V(n) asm volatile("s_waitcnt vmcnt(" #n ")" ::: "memory")
; #define PG8_WAIT_L(n) asm volatile("s_waitcnt lgkmcnt(" #n ")" ::: "memory")
; #define PG8_BAR __builtin_amdgcn_s_barrier()
; #define PG8_SCHED __builtin_amdgcn_sched_barrier(0)
; template <class Epi, class Sched, bool ALIGN_EPI = false, bool SP2 = false>
; __device__ __forceinline__ void gemm_phase(PG8_LAS unsigned char* lds, const Gemm g, const Sched& S, const Epi& E) {
;     ...
;             PG8_LDA(At, 1, 1); PG8_STAGE(PG8_SB(1, 0), b3, voffB); PG8_STAGE(PG8_SB(1, 1), b3 + hstepB, voffB); PG8_STAGE(PG8_SA(1, 0), a3, voffA);
;             PG8_WAIT_V(8); PG8_WAIT_L(0); PG8_BAR; PG8_MMA(1, 0, At, B0); PG8_MMA(1, 1, At, B1); PG8_BAR; PG8_SCHED;
;     ...
;         if constexpr (ALIGN_EPI) { if (wr == 0) PG8_BAR; }
	s_add_u32 s42, s40, 0x8000
	s_addc_u32 s43, s41, 0
	s_add_i32 s31, s31, s14
	v_lshl_add_u64 v[212:213], s[42:43], 0, v[220:221]
	s_mov_b32 m0, s31
	ds_read_b128 v[180:183], v174 offset:49152
	ds_read_b128 v[184:187], v174 offset:50176
	ds_read_b128 v[188:191], v174 offset:51200
	ds_read_b128 v[192:195], v174 offset:52224
	ds_read_b128 v[196:199], v174 offset:53248
	ds_read_b128 v[200:203], v174 offset:54272
	ds_read_b128 v[204:207], v174 offset:55296
	ds_read_b128 v[208:211], v174 offset:56320
	global_load_lds_dwordx4 v[212:213], off
	s_add_i32 m0, s31, 0x2000
	s_add_u32 s40, s40, 0xc000
	v_lshl_add_u64 v[212:213], s[42:43], 0, v[136:137]
	s_addc_u32 s41, s41, 0
	s_add_i32 s31, s44, s14
	global_load_lds_dwordx4 v[212:213], off
	v_lshl_add_u64 v[212:213], s[40:41], 0, v[220:221]
	s_mov_b32 m0, s31
	s_nop 0
	global_load_lds_dwordx4 v[212:213], off
	v_lshl_add_u64 v[212:213], s[40:41], 0, v[136:137]
	s_add_i32 m0, s31, 0x2000
	s_nop 0
	global_load_lds_dwordx4 v[212:213], off
	v_lshl_add_u64 v[212:213], s[38:39], 0, v[140:141]
	s_mov_b32 m0, s21
	s_nop 0
	global_load_lds_dwordx4 v[212:213], off
	v_lshl_add_u64 v[212:213], s[38:39], 0, v[138:139]
	s_mov_b32 m0, s22
	s_nop 0
	global_load_lds_dwordx4 v[212:213], off
	s_waitcnt vmcnt(8)
	s_waitcnt lgkmcnt(0)
	s_barrier
	s_setprio 1
	s_waitcnt lgkmcnt(0)
	v_mfma_f32_16x16x32_bf16 v[60:63], v[128:131], v[180:183], v[60:63]
	v_mfma_f32_16x16x32_bf16 v[60:63], v[132:135], v[184:187], v[60:63]
	v_mfma_f32_16x16x32_bf16 v[56:59], v[148:151], v[180:183], v[56:59]
	v_mfma_f32_16x16x32_bf16 v[56:59], v[152:155], v[184:187], v[56:59]
	v_mfma_f32_16x16x32_bf16 v[48:51], v[128:131], v[188:191], v[48:51]
	v_mfma_f32_16x16x32_bf16 v[48:51], v[132:135], v[192:195], v[48:51]
	v_mfma_f32_16x16x32_bf16 v[40:43], v[148:151], v[188:191], v[40:43]
	v_mfma_f32_16x16x32_bf16 v[40:43], v[152:155], v[192:195], v[40:43]
	v_mfma_f32_16x16x32_bf16 v[32:35], v[128:131], v[196:199], v[32:35]
	v_mfma_f32_16x16x32_bf16 v[32:35], v[132:135], v[200:203], v[32:35]
	v_mfma_f32_16x16x32_bf16 v[24:27], v[148:151], v[196:199], v[24:27]
	v_mfma_f32_16x16x32_bf16 v[24:27], v[152:155], v[200:203], v[24:27]
	v_mfma_f32_16x16x32_bf16 v[16:19], v[128:131], v[204:207], v[16:19]
	v_mfma_f32_16x16x32_bf16 v[16:19], v[132:135], v[208:211], v[16:19]
	v_mfma_f32_16x16x32_bf16 v[8:11], v[148:151], v[204:207], v[8:11]
	v_mfma_f32_16x16x32_bf16 v[8:11], v[152:155], v[208:211], v[8:11]
	s_setprio 0
	s_setprio 1
	v_mfma_f32_16x16x32_bf16 v[52:55], v[156:159], v[180:183], v[52:55]
	v_mfma_f32_16x16x32_bf16 v[52:55], v[160:163], v[184:187], v[52:55]
	v_mfma_f32_16x16x32_bf16 v[44:47], v[164:167], v[180:183], v[44:47]
	v_mfma_f32_16x16x32_bf16 v[44:47], v[176:179], v[184:187], v[44:47]
	v_mfma_f32_16x16x32_bf16 v[36:39], v[156:159], v[188:191], v[36:39]
	v_mfma_f32_16x16x32_bf16 v[36:39], v[160:163], v[192:195], v[36:39]
	v_mfma_f32_16x16x32_bf16 v[28:31], v[164:167], v[188:191], v[28:31]
	v_mfma_f32_16x16x32_bf16 v[28:31], v[176:179], v[192:195], v[28:31]
	v_mfma_f32_16x16x32_bf16 v[20:23], v[156:159], v[196:199], v[20:23]
	v_mfma_f32_16x16x32_bf16 v[20:23], v[160:163], v[200:203], v[20:23]
	v_mfma_f32_16x16x32_bf16 v[12:15], v[164:167], v[196:199], v[12:15]
	v_mfma_f32_16x16x32_bf16 v[12:15], v[176:179], v[200:203], v[12:15]
	v_mfma_f32_16x16x32_bf16 v[4:7], v[156:159], v[204:207], v[4:7]
	v_mfma_f32_16x16x32_bf16 v[4:7], v[160:163], v[208:211], v[4:7]
	v_mfma_f32_16x16x32_bf16 v[0:3], v[164:167], v[204:207], v[0:3]
	v_mfma_f32_16x16x32_bf16 v[0:3], v[176:179], v[208:211], v[0:3]
	s_setprio 2
	s_barrier
	s_add_i32 s30, s30, 2
	s_add_u32 s36, s36, 0x10000
	s_addc_u32 s37, s37, 0
	s_add_u32 s28, s28, 0x10000
	s_addc_u32 s29, s29, 0
	s_cmp_gt_u32 s30, 29
	s_cbranch_scc0 .LBB0_232
	s_and_b64 vcc, exec, s[8:9]
	s_cbranch_vccz .LBB0_235
	s_barrier

; #define PG8_STAGE(bufoff, gbase, voff) do { _Pragma("unroll") for (int _i = 0; _i < 2; ++_i) \
;         __builtin_amdgcn_global_load_lds((const unsigned*)((const char*)(gbase) + (voff)[_i]), (PG8_LAS unsigned*)(lds + (bufoff) + ldsw + _i * 8192), 16, 0, 0); } while (0)
; #define PG8_LDA(dst, b, h) do { _Pragma("unroll") for (int m = 0; m < 4; ++m) _Pragma("unroll") for (int k = 0; k < 2; ++k) dst[m][k] = *(const PG8_LAS bf16x8*)(lds + PG8_SA(b, h) + aoff + m * 2048 + k * 1024); } while (0)
; #define PG8_LDB(dst, b, h) do { _Pragma("unroll") for (int n = 0; n < 2; ++n) _Pragma("unroll") for (int k = 0; k < 2; ++k) dst[n][k] = *(const PG8_LAS bf16x8*)(lds + PG8_SB(b, h) + boff + n * 2048 + k * 1024); } while (0)
; #define PG8_MMA(ai, bj, At, Bt) do { __builtin_amdgcn_s_setprio(1); _Pragma("unroll") for (int m = 0; m < 4; ++m) _Pragma("unroll") for (int n = 0; n < 2; ++n) _Pragma("unroll") for (int k = 0; k < 2; ++k) \
;         acc[ai][bj][m][n] = __builtin_amdgcn_mfma_f32_16x16x32_bf16(Bt[n][k], At[m][k], acc[ai][bj][m][n], 0, 0, 0); __builtin_amdgcn_s_setprio(0); } while (0)
; #define PG8_WAIT_V(n) asm volatile("s_waitcnt vmcnt(" #n ")" ::: "memory")
; #define PG8_WAIT_L(n) asm volatile("s_waitcnt lgkmcnt(" #n ")" ::: "memory")
; #define PG8_BAR __builtin_amdgcn_s_barrier()
; #define PG8_SCHED __builtin_amdgcn_sched_barrier(0)
; template <class Epi, class Sched, bool ALIGN_EPI = false, bool SP2 = false>
; __device__ __forceinline__ void gemm_phase(PG8_LAS unsigned char* lds, const Gemm g, const Sched& S, const Epi& E) {
;     ...
;             const bool last = (t == nt - 2);
;             const char* a1 = cA + (size_t)(t + 1) * kstepB;
;             const char* a2 = last ? nA : cA + (size_t)(t + 2) * kstepB; const char* b2 = last ? nB : cB + (size_t)(t + 2) * kstepB;
;             const char* a3 = a2 + kstepB; const char* b3 = b2 + kstepB;
;             if (last && has_next) S.a_ready(nxt);
;             if constexpr (SP2) {
;             PG8_LDB(B0, 0, 0); PG8_LDB(B1, 0, 1); PG8_SCHED; PG8_LDA(At, 0, 0); PG8_STAGE(PG8_SA(1, 1), a1 + hstepB, voffA);
;             PG8_WAIT_V(8); PG8_WAIT_L(0); PG8_BAR; PG8_MMA(0, 0, At, B0); PG8_MMA(0, 1, At, B1); PG8_BAR; PG8_SCHED;
;             PG8_LDA(At, 0, 1); PG8_STAGE(PG8_SB(0, 0), b2, voffB); PG8_STAGE(PG8_SB(0, 1), b2 + hstepB, voffB); PG8_STAGE(PG8_SA(0, 0), a2, voffA);
.LBB0_263:
	s_add_u32 s38, s36, 0x4000
	s_addc_u32 s39, s37, 0
	s_cmp_eq_u32 s62, 28
	s_cselect_b32 s42, s30, s38
	s_cselect_b32 s43, s13, s39
	s_cselect_b32 s40, s31, s44
	s_cselect_b32 s41, s11, s45
	s_add_u32 s38, s42, 0x8000
	s_addc_u32 s39, s43, 0
	s_add_i32 s63, 0, 0x10000
	v_add_u32_e32 v151, s63, v165
	s_add_i32 s75, 0, 0x14000
	ds_read_b128 v[128:131], v151
	ds_read_b128 v[132:135], v151 offset:1024
	ds_read_b128 v[152:155], v151 offset:2048
	ds_read_b128 v[156:159], v151 offset:3072
	v_add_u32_e32 v151, s75, v165
	ds_read_b128 v[160:163], v151
	ds_read_b128 v[170:173], v151 offset:1024
	ds_read_b128 v[174:177], v151 offset:2048
	ds_read_b128 v[178:181], v151 offset:3072
	v_lshl_add_u64 v[214:215], s[36:37], 0, v[146:147]
	s_add_i32 m0, s19, 0xc000
	ds_read_b128 v[182:185], v168
	ds_read_b128 v[186:189], v168 offset:1024
	ds_read_b128 v[190:193], v168 offset:2048
	ds_read_b128 v[194:197], v168 offset:3072
	ds_read_b128 v[198:201], v168 offset:4096
	ds_read_b128 v[202:205], v168 offset:5120
	ds_read_b128 v[206:209], v168 offset:6144
	ds_read_b128 v[210:213], v168 offset:7168
	global_load_lds_dwordx4 v[214:215], off
	v_lshl_add_u64 v[214:215], s[36:37], 0, v[148:149]
	s_add_i32 m0, s19, 0xe000
	s_nop 0
	global_load_lds_dwordx4 v[214:215], off
	s_waitcnt vmcnt(8)
	s_waitcnt lgkmcnt(0)
	s_barrier
	s_setprio 1
	s_waitcnt lgkmcnt(0)
	v_mfma_f32_16x16x32_bf16 v[124:127], v[128:131], v[182:185], v[124:127]
	v_mfma_f32_16x16x32_bf16 v[124:127], v[132:135], v[186:189], v[124:127]
	v_mfma_f32_16x16x32_bf16 v[116:119], v[152:155], v[182:185], v[116:119]
	v_mfma_f32_16x16x32_bf16 v[116:119], v[156:159], v[186:189], v[116:119]
	v_mfma_f32_16x16x32_bf16 v[108:111], v[128:131], v[190:193], v[108:111]
	v_mfma_f32_16x16x32_bf16 v[108:111], v[132:135], v[194:197], v[108:111]
	v_mfma_f32_16x16x32_bf16 v[100:103], v[152:155], v[190:193], v[100:103]
	v_mfma_f32_16x16x32_bf16 v[100:103], v[156:159], v[194:197], v[100:103]
	v_mfma_f32_16x16x32_bf16 v[92:95], v[128:131], v[198:201], v[92:95]
	v_mfma_f32_16x16x32_bf16 v[92:95], v[132:135], v[202:205], v[92:95]
	v_mfma_f32_16x16x32_bf16 v[84:87], v[152:155], v[198:201], v[84:87]
	v_mfma_f32_16x16x32_bf16 v[84:87], v[156:159], v[202:205], v[84:87]
	v_mfma_f32_16x16x32_bf16 v[76:79], v[128:131], v[206:209], v[76:79]
	v_mfma_f32_16x16x32_bf16 v[76:79], v[132:135], v[210:213], v[76:79]
	v_mfma_f32_16x16x32_bf16 v[68:71], v[152:155], v[206:209], v[68:71]
	v_mfma_f32_16x16x32_bf16 v[68:71], v[156:159], v[210:213], v[68:71]
	s_setprio 0
	s_setprio 1
	v_mfma_f32_16x16x32_bf16 v[120:123], v[160:163], v[182:185], v[120:123]
	v_mfma_f32_16x16x32_bf16 v[120:123], v[170:173], v[186:189], v[120:123]
	v_mfma_f32_16x16x32_bf16 v[112:115], v[174:177], v[182:185], v[112:115]
	v_mfma_f32_16x16x32_bf16 v[112:115], v[178:181], v[186:189], v[112:115]
	v_mfma_f32_16x16x32_bf16 v[104:107], v[160:163], v[190:193], v[104:107]
	v_mfma_f32_16x16x32_bf16 v[104:107], v[170:173], v[194:197], v[104:107]
	v_mfma_f32_16x16x32_bf16 v[96:99], v[174:177], v[190:193], v[96:99]
	v_mfma_f32_16x16x32_bf16 v[96:99], v[178:181], v[194:197], v[96:99]
	v_mfma_f32_16x16x32_bf16 v[88:91], v[160:163], v[198:201], v[88:91]
	v_mfma_f32_16x16x32_bf16 v[88:91], v[170:173], v[202:205], v[88:91]
	v_mfma_f32_16x16x32_bf16 v[80:83], v[174:177], v[198:201], v[80:83]
	v_mfma_f32_16x16x32_bf16 v[80:83], v[178:181], v[202:205], v[80:83]
	v_mfma_f32_16x16x32_bf16 v[72:75], v[160:163], v[206:209], v[72:75]
	v_mfma_f32_16x16x32_bf16 v[72:75], v[170:173], v[210:213], v[72:75]
	v_mfma_f32_16x16x32_bf16 v[64:67], v[174:177], v[206:209], v[64:67]
	v_mfma_f32_16x16x32_bf16 v[64:67], v[178:181], v[210:213], v[64:67]
	s_setprio 2
	s_barrier
	s_add_i32 s63, s63, s16
	v_lshl_add_u64 v[214:215], s[40:41], 0, v[140:141]
	s_mov_b32 m0, s63
	ds_read_b128 v[182:185], v168 offset:16384
	ds_read_b128 v[186:189], v168 offset:17408
	ds_read_b128 v[190:193], v168 offset:18432
	ds_read_b128 v[194:197], v168 offset:19456
	ds_read_b128 v[198:201], v168 offset:20480
	ds_read_b128 v[202:205], v168 offset:21504
	ds_read_b128 v[206:209], v168 offset:22528
	ds_read_b128 v[210:213], v168 offset:23552
	global_load_lds_dwordx4 v[214:215], off
	s_add_i32 m0, s63, 0x2000
	s_add_u32 s66, s40, 0x4000
	v_lshl_add_u64 v[214:215], s[40:41], 0, v[136:137]
	s_addc_u32 s67, s41, 0
	s_add_i32 s63, s75, s16
	global_load_lds_dwordx4 v[214:215], off
	v_lshl_add_u64 v[214:215], s[66:67], 0, v[140:141]
	s_mov_b32 m0, s63
	s_nop 0
	global_load_lds_dwordx4 v[214:215], off
	v_lshl_add_u64 v[214:215], s[66:67], 0, v[136:137]
	s_add_i32 m0, s63, 0x2000
	s_nop 0
	global_load_lds_dwordx4 v[214:215], off
	v_lshl_add_u64 v[214:215], s[42:43], 0, v[142:143]
	s_mov_b32 m0, s19
	s_nop 0
	global_load_lds_dwordx4 v[214:215], off
	v_lshl_add_u64 v[214:215], s[42:43], 0, v[138:139]
	s_mov_b32 m0, s20
	s_nop 0
	global_load_lds_dwordx4 v[214:215], off
	s_waitcnt vmcnt(8)
	s_waitcnt lgkmcnt(0)
	s_barrier
; #define PG8_STAGE(bufoff, gbase, voff) do { _Pragma("unroll") for (int _i = 0; _i < 2; ++_i) \
;         __builtin_amdgcn_global_load_lds((const unsigned*)((const char*)(gbase) + (voff)[_i]), (PG8_LAS unsigned*)(lds + (bufoff) + ldsw + _i * 8192), 16, 0, 0); } while (0)
; #define PG8_LDA(dst, b, h) do { _Pragma("unroll") for (int m = 0; m < 4; ++m) _Pragma("unroll") for (int k = 0; k < 2; ++k) dst[m][k] = *(const PG8_LAS bf16x8*)(lds + PG8_SA(b, h) + aoff + m * 2048 + k * 1024); } while (0)
; #define PG8_LDB(dst, b, h) do { _Pragma("unroll") for (int n = 0; n < 2; ++n) _Pragma("unroll") for (int k = 0; k < 2; ++k) dst[n][k] = *(const PG8_LAS bf16x8*)(lds + PG8_SB(b, h) + boff + n * 2048 + k * 1024); } while (0)
; #define PG8_MMA(ai, bj, At, Bt) do { __builtin_amdgcn_s_setprio(1); _Pragma("unroll") for (int m = 0; m < 4; ++m) _Pragma("unroll") for (int n = 0; n < 2; ++n) _Pragma("unroll") for (int k = 0; k < 2; ++k) \
;         acc[ai][bj][m][n] = __builtin_amdgcn_mfma_f32_16x16x32_bf16(Bt[n][k], At[m][k], acc[ai][bj][m][n], 0, 0, 0); __builtin_amdgcn_s_setprio(0); } while (0)
; #define PG8_WAIT_V(n) asm volatile("s_waitcnt vmcnt(" #n ")" ::: "memory")
; #define PG8_WAIT_L(n) asm volatile("s_waitcnt lgkmcnt(" #n ")" ::: "memory")
; #define PG8_BAR __builtin_amdgcn_s_barrier()
; #define PG8_SCHED __builtin_amdgcn_sched_barrier(0)
; template <class Epi, class Sched, bool ALIGN_EPI = false, bool SP2 = false>
; __device__ __forceinline__ void gemm_phase(PG8_LAS unsigned char* lds, const Gemm g, const Sched& S, const Epi& E) {
;     ...
;             PG8_WAIT_V(8); PG8_WAIT_L(0); PG8_BAR; PG8_MMA(1, 0, At, B0); PG8_MMA(1, 1, At, B1); PG8_BAR; PG8_SCHED;
;             PG8_LDB(B0, 1, 0); PG8_LDB(B1, 1, 1); PG8_SCHED; PG8_LDA(At, 1, 0); PG8_STAGE(PG8_SA(0, 1), a2 + hstepB, voffA);
;             PG8_WAIT_V(8); PG8_WAIT_L(0); PG8_BAR; PG8_MMA(0, 0, At, B0); PG8_MMA(0, 1, At, B1); PG8_BAR; PG8_SCHED;
	s_setprio 1
	s_waitcnt lgkmcnt(0)
	v_mfma_f32_16x16x32_bf16 v[60:63], v[128:131], v[182:185], v[60:63]
	v_mfma_f32_16x16x32_bf16 v[60:63], v[132:135], v[186:189], v[60:63]
	v_mfma_f32_16x16x32_bf16 v[52:55], v[152:155], v[182:185], v[52:55]
	v_mfma_f32_16x16x32_bf16 v[52:55], v[156:159], v[186:189], v[52:55]
	v_mfma_f32_16x16x32_bf16 v[44:47], v[128:131], v[190:193], v[44:47]
	v_mfma_f32_16x16x32_bf16 v[44:47], v[132:135], v[194:197], v[44:47]
	v_mfma_f32_16x16x32_bf16 v[36:39], v[152:155], v[190:193], v[36:39]
	v_mfma_f32_16x16x32_bf16 v[36:39], v[156:159], v[194:197], v[36:39]
	v_mfma_f32_16x16x32_bf16 v[28:31], v[128:131], v[198:201], v[28:31]
	v_mfma_f32_16x16x32_bf16 v[28:31], v[132:135], v[202:205], v[28:31]
	v_mfma_f32_16x16x32_bf16 v[20:23], v[152:155], v[198:201], v[20:23]
	v_mfma_f32_16x16x32_bf16 v[20:23], v[156:159], v[202:205], v[20:23]
	v_mfma_f32_16x16x32_bf16 v[12:15], v[128:131], v[206:209], v[12:15]
	v_mfma_f32_16x16x32_bf16 v[12:15], v[132:135], v[210:213], v[12:15]
	v_mfma_f32_16x16x32_bf16 v[4:7], v[152:155], v[206:209], v[4:7]
	v_mfma_f32_16x16x32_bf16 v[4:7], v[156:159], v[210:213], v[4:7]
	s_setprio 0
	s_setprio 1
	v_mfma_f32_16x16x32_bf16 v[56:59], v[160:163], v[182:185], v[56:59]
	v_mfma_f32_16x16x32_bf16 v[56:59], v[170:173], v[186:189], v[56:59]
	v_mfma_f32_16x16x32_bf16 v[48:51], v[174:177], v[182:185], v[48:51]
	v_mfma_f32_16x16x32_bf16 v[48:51], v[178:181], v[186:189], v[48:51]
	v_mfma_f32_16x16x32_bf16 v[40:43], v[160:163], v[190:193], v[40:43]
	v_mfma_f32_16x16x32_bf16 v[40:43], v[170:173], v[194:197], v[40:43]
	v_mfma_f32_16x16x32_bf16 v[32:35], v[174:177], v[190:193], v[32:35]
	v_mfma_f32_16x16x32_bf16 v[32:35], v[178:181], v[194:197], v[32:35]
	v_mfma_f32_16x16x32_bf16 v[24:27], v[160:163], v[198:201], v[24:27]
	v_mfma_f32_16x16x32_bf16 v[24:27], v[170:173], v[202:205], v[24:27]
	v_mfma_f32_16x16x32_bf16 v[16:19], v[174:177], v[198:201], v[16:19]
	v_mfma_f32_16x16x32_bf16 v[16:19], v[178:181], v[202:205], v[16:19]
	v_mfma_f32_16x16x32_bf16 v[8:11], v[160:163], v[206:209], v[8:11]
	v_mfma_f32_16x16x32_bf16 v[8:11], v[170:173], v[210:213], v[8:11]
	v_mfma_f32_16x16x32_bf16 v[0:3], v[174:177], v[206:209], v[0:3]
	v_mfma_f32_16x16x32_bf16 v[0:3], v[178:181], v[210:213], v[0:3]
	s_setprio 2
	s_barrier
	s_add_i32 s63, 0, 0x18000
	v_add_u32_e32 v151, s63, v165
	s_add_i32 s66, 0, 0x1c000
	ds_read_b128 v[128:131], v151
	ds_read_b128 v[132:135], v151 offset:1024
	ds_read_b128 v[152:155], v151 offset:2048
	ds_read_b128 v[156:159], v151 offset:3072
	v_add_u32_e32 v151, s66, v165
	ds_read_b128 v[160:163], v151
	ds_read_b128 v[170:173], v151 offset:1024
	ds_read_b128 v[174:177], v151 offset:2048
	ds_read_b128 v[178:181], v151 offset:3072
	s_add_u32 s42, s42, 0x4000
	s_addc_u32 s43, s43, 0
	s_mov_b32 m0, s21
	v_lshl_add_u64 v[214:215], s[42:43], 0, v[142:143]
	ds_read_b128 v[182:185], v168 offset:32768
	ds_read_b128 v[186:189], v168 offset:33792
	ds_read_b128 v[190:193], v168 offset:34816
	ds_read_b128 v[194:197], v168 offset:35840
	ds_read_b128 v[198:201], v168 offset:36864
	ds_read_b128 v[202:205], v168 offset:37888
	ds_read_b128 v[206:209], v168 offset:38912
	ds_read_b128 v[210:213], v168 offset:39936
	global_load_lds_dwordx4 v[214:215], off
	v_lshl_add_u64 v[214:215], s[42:43], 0, v[138:139]
	s_mov_b32 m0, s22
	s_nop 0
	global_load_lds_dwordx4 v[214:215], off
	s_waitcnt vmcnt(8)
	s_waitcnt lgkmcnt(0)
	s_barrier
	s_setprio 1
	s_waitcnt lgkmcnt(0)
	v_mfma_f32_16x16x32_bf16 v[124:127], v[128:131], v[182:185], v[124:127]
	v_mfma_f32_16x16x32_bf16 v[124:127], v[132:135], v[186:189], v[124:127]
	v_mfma_f32_16x16x32_bf16 v[116:119], v[152:155], v[182:185], v[116:119]
	v_mfma_f32_16x16x32_bf16 v[116:119], v[156:159], v[186:189], v[116:119]
	v_mfma_f32_16x16x32_bf16 v[108:111], v[128:131], v[190:193], v[108:111]
	v_mfma_f32_16x16x32_bf16 v[108:111], v[132:135], v[194:197], v[108:111]
	v_mfma_f32_16x16x32_bf16 v[100:103], v[152:155], v[190:193], v[100:103]
	v_mfma_f32_16x16x32_bf16 v[100:103], v[156:159], v[194:197], v[100:103]
	v_mfma_f32_16x16x32_bf16 v[92:95], v[128:131], v[198:201], v[92:95]
	v_mfma_f32_16x16x32_bf16 v[92:95], v[132:135], v[202:205], v[92:95]
	v_mfma_f32_16x16x32_bf16 v[84:87], v[152:155], v[198:201], v[84:87]
	v_mfma_f32_16x16x32_bf16 v[84:87], v[156:159], v[202:205], v[84:87]
	v_mfma_f32_16x16x32_bf16 v[76:79], v[128:131], v[206:209], v[76:79]
	v_mfma_f32_16x16x32_bf16 v[76:79], v[132:135], v[210:213], v[76:79]
	v_mfma_f32_16x16x32_bf16 v[68:71], v[152:155], v[206:209], v[68:71]
	v_mfma_f32_16x16x32_bf16 v[68:71], v[156:159], v[210:213], v[68:71]
	s_setprio 0
	s_setprio 1
	v_mfma_f32_16x16x32_bf16 v[120:123], v[160:163], v[182:185], v[120:123]
	v_mfma_f32_16x16x32_bf16 v[120:123], v[170:173], v[186:189], v[120:123]
	v_mfma_f32_16x16x32_bf16 v[112:115], v[174:177], v[182:185], v[112:115]
	v_mfma_f32_16x16x32_bf16 v[112:115], v[178:181], v[186:189], v[112:115]
	v_mfma_f32_16x16x32_bf16 v[104:107], v[160:163], v[190:193], v[104:107]
	v_mfma_f32_16x16x32_bf16 v[104:107], v[170:173], v[194:197], v[104:107]
	v_mfma_f32_16x16x32_bf16 v[96:99], v[174:177], v[190:193], v[96:99]
	v_mfma_f32_16x16x32_bf16 v[96:99], v[178:181], v[194:197], v[96:99]
	v_mfma_f32_16x16x32_bf16 v[88:91], v[160:163], v[198:201], v[88:91]
	v_mfma_f32_16x16x32_bf16 v[88:91], v[170:173], v[202:205], v[88:91]
	v_mfma_f32_16x16x32_bf16 v[80:83], v[174:177], v[198:201], v[80:83]
	v_mfma_f32_16x16x32_bf16 v[80:83], v[178:181], v[202:205], v[80:83]
	v_mfma_f32_16x16x32_bf16 v[72:75], v[160:163], v[206:209], v[72:75]
	v_mfma_f32_16x16x32_bf16 v[72:75], v[170:173], v[210:213], v[72:75]
	v_mfma_f32_16x16x32_bf16 v[64:67], v[174:177], v[206:209], v[64:67]
	v_mfma_f32_16x16x32_bf16 v[64:67], v[178:181], v[210:213], v[64:67]
	s_setprio 2
	s_barrier
; #define PG8_STAGE(bufoff, gbase, voff) do { _Pragma("unroll") for (int _i = 0; _i < 2; ++_i) \
;         __builtin_amdgcn_global_load_lds((const unsigned*)((const char*)(gbase) + (voff)[_i]), (PG8_LAS unsigned*)(lds + (bufoff) + ldsw + _i * 8192), 16, 0, 0); } while (0)
; #define PG8_LDA(dst, b, h) do { _Pragma("unroll") for (int m = 0; m < 4; ++m) _Pragma("unroll") for (int k = 0; k < 2; ++k) dst[m][k] = *(const PG8_LAS bf16x8*)(lds + PG8_SA(b, h) + aoff + m * 2048 + k * 1024); } while (0)
; #define PG8_MMA(ai, bj, At, Bt) do { __builtin_amdgcn_s_setprio(1); _Pragma("unroll") for (int m = 0; m < 4; ++m) _Pragma("unroll") for (int n = 0; n < 2; ++n) _Pragma("unroll") for (int k = 0; k < 2; ++k) \
;         acc[ai][bj][m][n] = __builtin_amdgcn_mfma_f32_16x16x32_bf16(Bt[n][k], At[m][k], acc[ai][bj][m][n], 0, 0, 0); __builtin_amdgcn_s_setprio(0); } while (0)
; #define PG8_WAIT_V(n) asm volatile("s_waitcnt vmcnt(" #n ")" ::: "memory")
; #define PG8_WAIT_L(n) asm volatile("s_waitcnt lgkmcnt(" #n ")" ::: "memory")
; #define PG8_BAR __builtin_amdgcn_s_barrier()
; #define PG8_SCHED __builtin_amdgcn_sched_barrier(0)
; template <class Epi, class Sched, bool ALIGN_EPI = false, bool SP2 = false>
; __device__ __forceinline__ void gemm_phase(PG8_LAS unsigned char* lds, const Gemm g, const Sched& S, const Epi& E) {
;     ...
;             PG8_LDA(At, 1, 1); PG8_STAGE(PG8_SB(1, 0), b3, voffB); PG8_STAGE(PG8_SB(1, 1), b3 + hstepB, voffB); PG8_STAGE(PG8_SA(1, 0), a3, voffA);
;             PG8_WAIT_V(8); PG8_WAIT_L(0); PG8_BAR; PG8_MMA(1, 0, At, B0); PG8_MMA(1, 1, At, B1); PG8_BAR; PG8_SCHED;
;     ...
;         if constexpr (ALIGN_EPI) { if (wr == 0) PG8_BAR; }
	s_add_u32 s42, s40, 0x8000
	s_addc_u32 s43, s41, 0
	s_add_i32 s63, s63, s16
	v_lshl_add_u64 v[214:215], s[42:43], 0, v[140:141]
	s_mov_b32 m0, s63
	ds_read_b128 v[182:185], v168 offset:49152
	ds_read_b128 v[186:189], v168 offset:50176
	ds_read_b128 v[190:193], v168 offset:51200
	ds_read_b128 v[194:197], v168 offset:52224
	ds_read_b128 v[198:201], v168 offset:53248
	ds_read_b128 v[202:205], v168 offset:54272
	ds_read_b128 v[206:209], v168 offset:55296
	ds_read_b128 v[210:213], v168 offset:56320
	global_load_lds_dwordx4 v[214:215], off
	s_add_i32 m0, s63, 0x2000
	s_add_u32 s40, s40, 0xc000
	v_lshl_add_u64 v[214:215], s[42:43], 0, v[136:137]
	s_addc_u32 s41, s41, 0
	s_add_i32 s42, s66, s16
	global_load_lds_dwordx4 v[214:215], off
	v_lshl_add_u64 v[214:215], s[40:41], 0, v[140:141]
	s_mov_b32 m0, s42
	s_nop 0
	global_load_lds_dwordx4 v[214:215], off
	v_lshl_add_u64 v[214:215], s[40:41], 0, v[136:137]
	s_add_i32 m0, s42, 0x2000
	s_nop 0
	global_load_lds_dwordx4 v[214:215], off
	v_lshl_add_u64 v[214:215], s[38:39], 0, v[142:143]
	s_mov_b32 m0, s25
	s_nop 0
	global_load_lds_dwordx4 v[214:215], off
	v_lshl_add_u64 v[214:215], s[38:39], 0, v[138:139]
	s_mov_b32 m0, s26
	s_nop 0
	global_load_lds_dwordx4 v[214:215], off
	s_waitcnt vmcnt(8)
	s_waitcnt lgkmcnt(0)
	s_barrier
	s_setprio 1
	s_waitcnt lgkmcnt(0)
	v_mfma_f32_16x16x32_bf16 v[60:63], v[128:131], v[182:185], v[60:63]
	v_mfma_f32_16x16x32_bf16 v[60:63], v[132:135], v[186:189], v[60:63]
	v_mfma_f32_16x16x32_bf16 v[52:55], v[152:155], v[182:185], v[52:55]
	v_mfma_f32_16x16x32_bf16 v[52:55], v[156:159], v[186:189], v[52:55]
	v_mfma_f32_16x16x32_bf16 v[44:47], v[128:131], v[190:193], v[44:47]
	v_mfma_f32_16x16x32_bf16 v[44:47], v[132:135], v[194:197], v[44:47]
	v_mfma_f32_16x16x32_bf16 v[36:39], v[152:155], v[190:193], v[36:39]
	v_mfma_f32_16x16x32_bf16 v[36:39], v[156:159], v[194:197], v[36:39]
	v_mfma_f32_16x16x32_bf16 v[28:31], v[128:131], v[198:201], v[28:31]
	v_mfma_f32_16x16x32_bf16 v[28:31], v[132:135], v[202:205], v[28:31]
	v_mfma_f32_16x16x32_bf16 v[20:23], v[152:155], v[198:201], v[20:23]
	v_mfma_f32_16x16x32_bf16 v[20:23], v[156:159], v[202:205], v[20:23]
	v_mfma_f32_16x16x32_bf16 v[12:15], v[128:131], v[206:209], v[12:15]
	v_mfma_f32_16x16x32_bf16 v[12:15], v[132:135], v[210:213], v[12:15]
	v_mfma_f32_16x16x32_bf16 v[4:7], v[152:155], v[206:209], v[4:7]
	v_mfma_f32_16x16x32_bf16 v[4:7], v[156:159], v[210:213], v[4:7]
	s_setprio 0
	s_setprio 1
	v_mfma_f32_16x16x32_bf16 v[56:59], v[160:163], v[182:185], v[56:59]
	v_mfma_f32_16x16x32_bf16 v[56:59], v[170:173], v[186:189], v[56:59]
	v_mfma_f32_16x16x32_bf16 v[48:51], v[174:177], v[182:185], v[48:51]
	v_mfma_f32_16x16x32_bf16 v[48:51], v[178:181], v[186:189], v[48:51]
	v_mfma_f32_16x16x32_bf16 v[40:43], v[160:163], v[190:193], v[40:43]
	v_mfma_f32_16x16x32_bf16 v[40:43], v[170:173], v[194:197], v[40:43]
	v_mfma_f32_16x16x32_bf16 v[32:35], v[174:177], v[190:193], v[32:35]
	v_mfma_f32_16x16x32_bf16 v[32:35], v[178:181], v[194:197], v[32:35]
	v_mfma_f32_16x16x32_bf16 v[24:27], v[160:163], v[198:201], v[24:27]
	v_mfma_f32_16x16x32_bf16 v[24:27], v[170:173], v[202:205], v[24:27]
	v_mfma_f32_16x16x32_bf16 v[16:19], v[174:177], v[198:201], v[16:19]
	v_mfma_f32_16x16x32_bf16 v[16:19], v[178:181], v[202:205], v[16:19]
	v_mfma_f32_16x16x32_bf16 v[8:11], v[160:163], v[206:209], v[8:11]
	v_mfma_f32_16x16x32_bf16 v[8:11], v[170:173], v[210:213], v[8:11]
	v_mfma_f32_16x16x32_bf16 v[0:3], v[174:177], v[206:209], v[0:3]
	v_mfma_f32_16x16x32_bf16 v[0:3], v[178:181], v[210:213], v[0:3]
	s_setprio 2
	s_barrier
	s_add_i32 s62, s62, 2
	s_add_u32 s36, s36, 0x10000
	s_addc_u32 s37, s37, 0
	s_add_u32 s44, s44, 0x10000
	s_addc_u32 s45, s45, 0
	s_cmp_gt_u32 s62, 29
	s_cbranch_scc0 .LBB0_263
	s_and_b64 vcc, exec, s[8:9]
	s_cbranch_vccz .LBB0_266
	s_barrier
